# E4p + q_b GEMM epilogue: second-half vmcnt(0) wait moved onto the rotary-load path only
# baseline (speedup 1.0000x reference)
.LBB0_752:
	s_waitcnt vmcnt(0)
	v_fmamk_f32 v128, v203, 0x3b000000, v196
	v_rsq_f32_e32 v128, v128
	v_fmamk_f32 v178, v205, 0x3b000000, v196
	v_rsq_f32_e32 v179, v178
	v_fmamk_f32 v178, v206, 0x3b000000, v196
	v_fmamk_f32 v131, v204, 0x3b000000, v196
	v_rsq_f32_e32 v181, v178
	v_mul_f32_e32 v178, 0x3dd53b94, v128
	v_rsq_f32_e32 v131, v131
	v_pk_mul_f32 v[120:121], v[120:121], v[178:179] op_sel_hi:[1,0]
	v_pk_mul_f32 v[124:125], v[124:125], v[178:179] op_sel_hi:[1,0]
	v_pk_mul_f32 v[122:123], v[122:123], v[178:179] op_sel_hi:[1,0]
	v_pk_mul_f32 v[208:209], v[120:121], v[156:157]
	v_pk_mul_f32 v[126:127], v[126:127], v[178:179] op_sel_hi:[1,0]
	v_pk_fma_f32 v[208:209], v[124:125], v[160:161], v[208:209] neg_lo:[0,0,1] neg_hi:[0,0,1]
	v_pk_mul_f32 v[210:211], v[122:123], v[162:163]
	v_pk_mul_f32 v[212:213], v[120:121], v[160:161]
	v_pk_mul_f32 v[206:207], v[122:123], v[158:159]
	v_pk_fma_f32 v[212:213], v[124:125], v[156:157], v[212:213]
	v_pk_fma_f32 v[210:211], v[126:127], v[158:159], v[210:211]
	v_cndmask_b32_e64 v124, v208, v124, s[8:9]
	v_mul_f32_e32 v180, 0x3dd53b94, v131
	v_mul_f32_e32 v204, 0x3dd53b94, v179
	v_lshl_or_b32 v131, s14, 8, v187
	v_pk_fma_f32 v[206:207], v[126:127], v[162:163], v[206:207] neg_lo:[0,0,1] neg_hi:[0,0,1]
	v_cndmask_b32_e64 v125, v209, v125, s[8:9]
	v_cndmask_b32_e64 v179, v210, v122, s[8:9]
	v_cndmask_b32_e64 v123, v211, v123, s[8:9]
	v_cndmask_b32_e64 v122, v212, v120, s[8:9]
	v_cvt_pk_bf16_f32 v120, v124, v125
	v_mul_lo_u32 v124, v176, s26
	v_add_u32_e32 v130, 0x80, v176
	v_mul_f32_e32 v128, 0x3dd53b94, v181
	v_cndmask_b32_e64 v126, v206, v126, s[8:9]
	v_cndmask_b32_e64 v127, v207, v127, s[8:9]
	v_cndmask_b32_e64 v181, v213, v121, s[8:9]
	v_cvt_pk_bf16_f32 v121, v126, v127
	v_cvt_pk_bf16_f32 v122, v122, v181
	v_cvt_pk_bf16_f32 v123, v179, v123
	v_add_lshl_u32 v176, v124, v131, 1
	v_pk_mul_f32 v[112:113], v[112:113], v[178:179] op_sel_hi:[1,0]
	v_pk_mul_f32 v[114:115], v[114:115], v[178:179] op_sel_hi:[1,0]
	global_store_dwordx4 v176, v[120:123], s[66:67]
	v_pk_mul_f32 v[116:117], v[116:117], v[178:179] op_sel_hi:[1,0]
	v_pk_mul_f32 v[118:119], v[118:119], v[178:179] op_sel_hi:[1,0]
	v_pk_mul_f32 v[120:121], v[114:115], v[158:159]
	v_pk_mul_f32 v[122:123], v[112:113], v[156:157]
	v_pk_mul_f32 v[124:125], v[114:115], v[162:163]
	v_pk_mul_f32 v[126:127], v[112:113], v[160:161]
	v_pk_fma_f32 v[122:123], v[116:117], v[160:161], v[122:123] neg_lo:[0,0,1] neg_hi:[0,0,1]
	v_pk_fma_f32 v[120:121], v[118:119], v[162:163], v[120:121] neg_lo:[0,0,1] neg_hi:[0,0,1]
	v_pk_fma_f32 v[126:127], v[116:117], v[156:157], v[126:127]
	v_pk_fma_f32 v[124:125], v[118:119], v[158:159], v[124:125]
	v_cndmask_b32_e64 v118, v120, v118, s[8:9]
	v_cndmask_b32_e64 v116, v122, v116, s[8:9]
	v_cndmask_b32_e64 v120, v124, v114, s[8:9]
	v_cndmask_b32_e64 v115, v125, v115, s[8:9]
	v_cndmask_b32_e64 v114, v126, v112, s[8:9]
	v_cndmask_b32_e64 v119, v121, v119, s[8:9]
	v_cndmask_b32_e64 v117, v123, v117, s[8:9]
	v_cndmask_b32_e64 v121, v127, v113, s[8:9]
	v_cvt_pk_bf16_f32 v112, v116, v117
	v_cvt_pk_bf16_f32 v113, v118, v119
	v_cvt_pk_bf16_f32 v114, v114, v121
	v_cvt_pk_bf16_f32 v115, v120, v115
	v_or_b32_e32 v116, 0x100, v176
	v_pk_mul_f32 v[104:105], v[104:105], v[180:181] op_sel_hi:[1,0]
	v_pk_mul_f32 v[106:107], v[106:107], v[180:181] op_sel_hi:[1,0]
	global_store_dwordx4 v116, v[112:115], s[66:67]
	v_pk_mul_f32 v[108:109], v[108:109], v[180:181] op_sel_hi:[1,0]
	v_pk_mul_f32 v[110:111], v[110:111], v[180:181] op_sel_hi:[1,0]
	v_pk_mul_f32 v[112:113], v[106:107], v[150:151]
	v_pk_mul_f32 v[114:115], v[104:105], v[148:149]
	v_pk_mul_f32 v[116:117], v[106:107], v[154:155]
	v_pk_mul_f32 v[118:119], v[104:105], v[152:153]
	v_pk_fma_f32 v[114:115], v[108:109], v[152:153], v[114:115] neg_lo:[0,0,1] neg_hi:[0,0,1]
	v_pk_fma_f32 v[112:113], v[110:111], v[154:155], v[112:113] neg_lo:[0,0,1] neg_hi:[0,0,1]
	v_pk_fma_f32 v[118:119], v[108:109], v[148:149], v[118:119]
	v_pk_fma_f32 v[116:117], v[110:111], v[150:151], v[116:117]
	v_cndmask_b32_e64 v110, v112, v110, s[8:9]
	v_cndmask_b32_e64 v108, v114, v108, s[8:9]
	v_cndmask_b32_e64 v112, v116, v106, s[8:9]
	v_cndmask_b32_e64 v107, v117, v107, s[8:9]
	v_cndmask_b32_e64 v106, v118, v104, s[8:9]
	v_cndmask_b32_e64 v111, v113, v111, s[8:9]
	v_cndmask_b32_e64 v109, v115, v109, s[8:9]
	v_cndmask_b32_e64 v113, v119, v105, s[8:9]
	v_cvt_pk_bf16_f32 v104, v108, v109
	v_cvt_pk_bf16_f32 v105, v110, v111
	v_cvt_pk_bf16_f32 v106, v106, v113
	v_cvt_pk_bf16_f32 v107, v112, v107
	v_add_u32_e32 v108, 0x18000, v176
	v_pk_mul_f32 v[96:97], v[96:97], v[180:181] op_sel_hi:[1,0]
	v_pk_mul_f32 v[98:99], v[98:99], v[180:181] op_sel_hi:[1,0]
	global_store_dwordx4 v108, v[104:107], s[66:67]
	v_pk_mul_f32 v[100:101], v[100:101], v[180:181] op_sel_hi:[1,0]
	v_pk_mul_f32 v[102:103], v[102:103], v[180:181] op_sel_hi:[1,0]
	v_pk_mul_f32 v[104:105], v[98:99], v[150:151]
	v_pk_mul_f32 v[106:107], v[96:97], v[148:149]
	v_pk_mul_f32 v[108:109], v[98:99], v[154:155]
	v_pk_mul_f32 v[110:111], v[96:97], v[152:153]
	v_pk_fma_f32 v[106:107], v[100:101], v[152:153], v[106:107] neg_lo:[0,0,1] neg_hi:[0,0,1]
	v_pk_fma_f32 v[104:105], v[102:103], v[154:155], v[104:105] neg_lo:[0,0,1] neg_hi:[0,0,1]
	v_pk_fma_f32 v[110:111], v[100:101], v[148:149], v[110:111]
	v_pk_fma_f32 v[108:109], v[102:103], v[150:151], v[108:109]
	v_cndmask_b32_e64 v102, v104, v102, s[8:9]
	v_cndmask_b32_e64 v100, v106, v100, s[8:9]
	v_cndmask_b32_e64 v104, v108, v98, s[8:9]
	v_cndmask_b32_e64 v99, v109, v99, s[8:9]
	v_cndmask_b32_e64 v98, v110, v96, s[8:9]
	v_cndmask_b32_e64 v103, v105, v103, s[8:9]
	v_cndmask_b32_e64 v101, v107, v101, s[8:9]
	v_cndmask_b32_e64 v105, v111, v97, s[8:9]
	v_cvt_pk_bf16_f32 v96, v100, v101
	v_cvt_pk_bf16_f32 v97, v102, v103
	v_cvt_pk_bf16_f32 v98, v98, v105
	v_cvt_pk_bf16_f32 v99, v104, v99
	v_add_u32_e32 v100, 0x18100, v176
	v_pk_mul_f32 v[88:89], v[88:89], v[204:205] op_sel_hi:[1,0]
	v_pk_mul_f32 v[90:91], v[90:91], v[204:205] op_sel_hi:[1,0]
	global_store_dwordx4 v100, v[96:99], s[66:67]
	v_pk_mul_f32 v[92:93], v[92:93], v[204:205] op_sel_hi:[1,0]
	v_pk_mul_f32 v[94:95], v[94:95], v[204:205] op_sel_hi:[1,0]
	v_pk_mul_f32 v[96:97], v[90:91], v[142:143]
	v_pk_mul_f32 v[98:99], v[88:89], v[140:141]
	v_pk_mul_f32 v[100:101], v[90:91], v[146:147]
	v_pk_mul_f32 v[102:103], v[88:89], v[144:145]
	v_pk_fma_f32 v[98:99], v[92:93], v[144:145], v[98:99] neg_lo:[0,0,1] neg_hi:[0,0,1]
	v_pk_fma_f32 v[96:97], v[94:95], v[146:147], v[96:97] neg_lo:[0,0,1] neg_hi:[0,0,1]
	v_pk_fma_f32 v[102:103], v[92:93], v[140:141], v[102:103]
	v_pk_fma_f32 v[100:101], v[94:95], v[142:143], v[100:101]
	v_cndmask_b32_e64 v94, v96, v94, s[8:9]
	v_cndmask_b32_e64 v92, v98, v92, s[8:9]
	v_cndmask_b32_e64 v96, v100, v90, s[8:9]
	v_cndmask_b32_e64 v91, v101, v91, s[8:9]
	v_cndmask_b32_e64 v90, v102, v88, s[8:9]
	v_cndmask_b32_e64 v95, v97, v95, s[8:9]
	v_cndmask_b32_e64 v93, v99, v93, s[8:9]
	v_cndmask_b32_e64 v97, v103, v89, s[8:9]
	v_cvt_pk_bf16_f32 v88, v92, v93
	v_cvt_pk_bf16_f32 v89, v94, v95
	v_cvt_pk_bf16_f32 v90, v90, v97
	v_cvt_pk_bf16_f32 v91, v96, v91
	v_add_u32_e32 v92, 0x30000, v176
	v_pk_mul_f32 v[80:81], v[80:81], v[204:205] op_sel_hi:[1,0]
	v_pk_mul_f32 v[82:83], v[82:83], v[204:205] op_sel_hi:[1,0]
	global_store_dwordx4 v92, v[88:91], s[66:67]
	v_pk_mul_f32 v[84:85], v[84:85], v[204:205] op_sel_hi:[1,0]
	v_pk_mul_f32 v[86:87], v[86:87], v[204:205] op_sel_hi:[1,0]
	v_pk_mul_f32 v[88:89], v[82:83], v[142:143]
	v_pk_mul_f32 v[90:91], v[80:81], v[140:141]
	v_pk_mul_f32 v[92:93], v[82:83], v[146:147]
	v_pk_mul_f32 v[94:95], v[80:81], v[144:145]
	v_pk_fma_f32 v[90:91], v[84:85], v[144:145], v[90:91] neg_lo:[0,0,1] neg_hi:[0,0,1]
	v_pk_fma_f32 v[88:89], v[86:87], v[146:147], v[88:89] neg_lo:[0,0,1] neg_hi:[0,0,1]
	v_pk_fma_f32 v[94:95], v[84:85], v[140:141], v[94:95]
	v_pk_fma_f32 v[92:93], v[86:87], v[142:143], v[92:93]
	v_cndmask_b32_e64 v86, v88, v86, s[8:9]
	v_cndmask_b32_e64 v84, v90, v84, s[8:9]
	v_cndmask_b32_e64 v88, v92, v82, s[8:9]
	v_cndmask_b32_e64 v83, v93, v83, s[8:9]
	v_cndmask_b32_e64 v82, v94, v80, s[8:9]
	v_cndmask_b32_e64 v87, v89, v87, s[8:9]
	v_cndmask_b32_e64 v85, v91, v85, s[8:9]
	v_cndmask_b32_e64 v89, v95, v81, s[8:9]
	v_cvt_pk_bf16_f32 v80, v84, v85
	v_cvt_pk_bf16_f32 v81, v86, v87
	v_cvt_pk_bf16_f32 v82, v82, v89
	v_cvt_pk_bf16_f32 v83, v88, v83
	v_add_u32_e32 v84, 0x30100, v176
	v_pk_mul_f32 v[72:73], v[72:73], v[128:129] op_sel_hi:[1,0]
	v_pk_mul_f32 v[74:75], v[74:75], v[128:129] op_sel_hi:[1,0]
	global_store_dwordx4 v84, v[80:83], s[66:67]
	v_pk_mul_f32 v[76:77], v[76:77], v[128:129] op_sel_hi:[1,0]
	v_pk_mul_f32 v[78:79], v[78:79], v[128:129] op_sel_hi:[1,0]
	v_pk_mul_f32 v[80:81], v[74:75], v[134:135]
	v_pk_mul_f32 v[82:83], v[72:73], v[132:133]
	v_pk_mul_f32 v[84:85], v[74:75], v[138:139]
	v_pk_mul_f32 v[86:87], v[72:73], v[136:137]
	v_pk_fma_f32 v[82:83], v[76:77], v[136:137], v[82:83] neg_lo:[0,0,1] neg_hi:[0,0,1]
	v_pk_fma_f32 v[80:81], v[78:79], v[138:139], v[80:81] neg_lo:[0,0,1] neg_hi:[0,0,1]
	v_pk_fma_f32 v[86:87], v[76:77], v[132:133], v[86:87]
	v_pk_fma_f32 v[84:85], v[78:79], v[134:135], v[84:85]
	v_cndmask_b32_e64 v78, v80, v78, s[8:9]
	v_cndmask_b32_e64 v76, v82, v76, s[8:9]
	v_cndmask_b32_e64 v80, v84, v74, s[8:9]
	v_cndmask_b32_e64 v75, v85, v75, s[8:9]
	v_cndmask_b32_e64 v74, v86, v72, s[8:9]
	v_cndmask_b32_e64 v79, v81, v79, s[8:9]
	v_cndmask_b32_e64 v77, v83, v77, s[8:9]
	v_cndmask_b32_e64 v81, v87, v73, s[8:9]
	v_cvt_pk_bf16_f32 v72, v76, v77
	v_cvt_pk_bf16_f32 v73, v78, v79
	v_cvt_pk_bf16_f32 v74, v74, v81
	v_cvt_pk_bf16_f32 v75, v80, v75
	v_add_u32_e32 v76, 0x48000, v176
	v_pk_mul_f32 v[64:65], v[64:65], v[128:129] op_sel_hi:[1,0]
	global_store_dwordx4 v76, v[72:75], s[66:67]
	v_pk_mul_f32 v[68:69], v[68:69], v[128:129] op_sel_hi:[1,0]
	v_pk_mul_f32 v[66:67], v[66:67], v[128:129] op_sel_hi:[1,0]
	v_pk_mul_f32 v[74:75], v[64:65], v[132:133]
	v_pk_mul_f32 v[70:71], v[70:71], v[128:129] op_sel_hi:[1,0]
	v_pk_mul_f32 v[72:73], v[66:67], v[134:135]
	v_pk_fma_f32 v[74:75], v[68:69], v[136:137], v[74:75] neg_lo:[0,0,1] neg_hi:[0,0,1]
	v_pk_mul_f32 v[76:77], v[66:67], v[138:139]
	v_pk_mul_f32 v[78:79], v[64:65], v[136:137]
	v_pk_fma_f32 v[72:73], v[70:71], v[138:139], v[72:73] neg_lo:[0,0,1] neg_hi:[0,0,1]
	v_pk_fma_f32 v[78:79], v[68:69], v[132:133], v[78:79]
	v_pk_fma_f32 v[76:77], v[70:71], v[134:135], v[76:77]
	v_cndmask_b32_e64 v68, v74, v68, s[8:9]
	v_cndmask_b32_e64 v70, v72, v70, s[8:9]
	v_cndmask_b32_e64 v69, v75, v69, s[8:9]
	v_cndmask_b32_e64 v72, v76, v66, s[8:9]
	v_cndmask_b32_e64 v67, v77, v67, s[8:9]
	v_cndmask_b32_e64 v66, v78, v64, s[8:9]
	v_cvt_pk_bf16_f32 v64, v68, v69
	v_add_u32_e32 v68, 0x48100, v176
	v_cndmask_b32_e64 v71, v73, v71, s[8:9]
	v_cndmask_b32_e64 v73, v79, v65, s[8:9]
	v_cvt_pk_bf16_f32 v65, v70, v71
	v_cvt_pk_bf16_f32 v66, v66, v73
	v_cvt_pk_bf16_f32 v67, v72, v67
	global_store_dwordx4 v68, v[64:67], s[66:67]
	s_andn2_b64 vcc, exec, s[82:83]
	s_cbranch_vccnz .LBB0_754
	v_lshl_or_b32 v64, v130, 7, s54
	v_or_b32_e32 v65, v64, v185
	global_load_dwordx4 v[160:163], v65, s[68:69]
	global_load_dwordx4 v[156:159], v65, s[70:71]
	v_add_u32_e32 v65, v188, v64
	global_load_dwordx4 v[152:155], v65, s[68:69]
	global_load_dwordx4 v[148:151], v65, s[70:71]
	v_add_u32_e32 v65, v189, v64
	v_add_u32_e32 v64, v190, v64
	global_load_dwordx4 v[144:147], v65, s[68:69]
	global_load_dwordx4 v[140:143], v65, s[70:71]
	global_load_dwordx4 v[136:139], v64, s[68:69]
	global_load_dwordx4 v[132:135], v64, s[70:71]
	s_waitcnt vmcnt(0)
.LBB0_754:
	v_fmamk_f32 v66, v193, 0x3b000000, v196
	v_rsq_f32_e32 v67, v66
	v_fmamk_f32 v66, v177, 0x3b000000, v196
	v_rsq_f32_e32 v69, v66
	v_fmamk_f32 v65, v194, 0x3b000000, v196
	v_rsq_f32_e32 v65, v65
	v_mul_f32_e32 v68, 0x3dd53b94, v67
	v_mul_f32_e32 v70, 0x3dd53b94, v69
	v_pk_mul_f32 v[56:57], v[56:57], v[70:71] op_sel_hi:[1,0]
	v_pk_mul_f32 v[60:61], v[60:61], v[70:71] op_sel_hi:[1,0]
	v_pk_mul_f32 v[58:59], v[58:59], v[70:71] op_sel_hi:[1,0]
	v_pk_mul_f32 v[74:75], v[56:57], v[156:157]
	v_pk_mul_f32 v[62:63], v[62:63], v[70:71] op_sel_hi:[1,0]
	v_pk_fma_f32 v[74:75], v[60:61], v[160:161], v[74:75] neg_lo:[0,0,1] neg_hi:[0,0,1]
	v_pk_mul_f32 v[76:77], v[58:59], v[162:163]
	v_pk_mul_f32 v[78:79], v[56:57], v[160:161]
	v_pk_mul_f32 v[72:73], v[58:59], v[158:159]
	v_pk_fma_f32 v[78:79], v[60:61], v[156:157], v[78:79]
	v_pk_fma_f32 v[76:77], v[62:63], v[158:159], v[76:77]
	v_cndmask_b32_e64 v60, v74, v60, s[8:9]
	v_mul_f32_e32 v66, 0x3dd53b94, v65
	v_pk_fma_f32 v[72:73], v[62:63], v[162:163], v[72:73] neg_lo:[0,0,1] neg_hi:[0,0,1]
	v_cndmask_b32_e64 v61, v75, v61, s[8:9]
	v_cndmask_b32_e64 v65, v76, v58, s[8:9]
	v_cndmask_b32_e64 v59, v77, v59, s[8:9]
	v_cndmask_b32_e64 v58, v78, v56, s[8:9]
	v_cvt_pk_bf16_f32 v56, v60, v61
	v_mul_lo_u32 v60, v130, s26
	v_cndmask_b32_e64 v62, v72, v62, s[8:9]
	v_cndmask_b32_e64 v63, v73, v63, s[8:9]
	v_cndmask_b32_e64 v67, v79, v57, s[8:9]
	v_cvt_pk_bf16_f32 v57, v62, v63
	v_cvt_pk_bf16_f32 v58, v58, v67
	v_cvt_pk_bf16_f32 v59, v65, v59
	v_add_lshl_u32 v65, v60, v131, 1
	v_pk_mul_f32 v[48:49], v[48:49], v[70:71] op_sel_hi:[1,0]
	v_pk_mul_f32 v[50:51], v[50:51], v[70:71] op_sel_hi:[1,0]
	global_store_dwordx4 v65, v[56:59], s[66:67]
	v_pk_mul_f32 v[52:53], v[52:53], v[70:71] op_sel_hi:[1,0]
	v_pk_mul_f32 v[54:55], v[54:55], v[70:71] op_sel_hi:[1,0]
	v_pk_mul_f32 v[56:57], v[50:51], v[158:159]
	v_pk_mul_f32 v[58:59], v[48:49], v[156:157]
	v_pk_mul_f32 v[60:61], v[50:51], v[162:163]
	v_pk_mul_f32 v[62:63], v[48:49], v[160:161]
	v_pk_fma_f32 v[58:59], v[52:53], v[160:161], v[58:59] neg_lo:[0,0,1] neg_hi:[0,0,1]
	v_pk_fma_f32 v[56:57], v[54:55], v[162:163], v[56:57] neg_lo:[0,0,1] neg_hi:[0,0,1]
	v_pk_fma_f32 v[62:63], v[52:53], v[156:157], v[62:63]
	v_pk_fma_f32 v[60:61], v[54:55], v[158:159], v[60:61]
	v_cndmask_b32_e64 v54, v56, v54, s[8:9]
	v_cndmask_b32_e64 v52, v58, v52, s[8:9]
	v_cndmask_b32_e64 v56, v60, v50, s[8:9]
	v_cndmask_b32_e64 v51, v61, v51, s[8:9]
	v_cndmask_b32_e64 v50, v62, v48, s[8:9]
	v_cndmask_b32_e64 v55, v57, v55, s[8:9]
	v_cndmask_b32_e64 v53, v59, v53, s[8:9]
	v_cndmask_b32_e64 v57, v63, v49, s[8:9]
	v_cvt_pk_bf16_f32 v48, v52, v53
	v_cvt_pk_bf16_f32 v49, v54, v55
	v_cvt_pk_bf16_f32 v50, v50, v57
	v_cvt_pk_bf16_f32 v51, v56, v51
	v_or_b32_e32 v52, 0x100, v65
	v_pk_mul_f32 v[40:41], v[40:41], v[68:69] op_sel_hi:[1,0]
	v_pk_mul_f32 v[42:43], v[42:43], v[68:69] op_sel_hi:[1,0]
	global_store_dwordx4 v52, v[48:51], s[66:67]
	v_pk_mul_f32 v[44:45], v[44:45], v[68:69] op_sel_hi:[1,0]
	v_pk_mul_f32 v[46:47], v[46:47], v[68:69] op_sel_hi:[1,0]
	v_pk_mul_f32 v[48:49], v[42:43], v[150:151]
	v_pk_mul_f32 v[50:51], v[40:41], v[148:149]
	v_pk_mul_f32 v[52:53], v[42:43], v[154:155]
	v_pk_mul_f32 v[54:55], v[40:41], v[152:153]
	v_pk_fma_f32 v[50:51], v[44:45], v[152:153], v[50:51] neg_lo:[0,0,1] neg_hi:[0,0,1]
	v_pk_fma_f32 v[48:49], v[46:47], v[154:155], v[48:49] neg_lo:[0,0,1] neg_hi:[0,0,1]
	v_pk_fma_f32 v[54:55], v[44:45], v[148:149], v[54:55]
	v_pk_fma_f32 v[52:53], v[46:47], v[150:151], v[52:53]
	v_cndmask_b32_e64 v46, v48, v46, s[8:9]
	v_cndmask_b32_e64 v44, v50, v44, s[8:9]
	v_cndmask_b32_e64 v48, v52, v42, s[8:9]
	v_cndmask_b32_e64 v43, v53, v43, s[8:9]
	v_cndmask_b32_e64 v42, v54, v40, s[8:9]
	v_cndmask_b32_e64 v47, v49, v47, s[8:9]
	v_cndmask_b32_e64 v45, v51, v45, s[8:9]
	v_cndmask_b32_e64 v49, v55, v41, s[8:9]
	v_cvt_pk_bf16_f32 v40, v44, v45
	v_cvt_pk_bf16_f32 v41, v46, v47
	v_cvt_pk_bf16_f32 v42, v42, v49
	v_cvt_pk_bf16_f32 v43, v48, v43
	v_add_u32_e32 v44, 0x18000, v65
	v_pk_mul_f32 v[32:33], v[32:33], v[68:69] op_sel_hi:[1,0]
	v_pk_mul_f32 v[34:35], v[34:35], v[68:69] op_sel_hi:[1,0]
	global_store_dwordx4 v44, v[40:43], s[66:67]
	v_pk_mul_f32 v[36:37], v[36:37], v[68:69] op_sel_hi:[1,0]
	v_pk_mul_f32 v[38:39], v[38:39], v[68:69] op_sel_hi:[1,0]
	v_pk_mul_f32 v[40:41], v[34:35], v[150:151]
	v_pk_mul_f32 v[42:43], v[32:33], v[148:149]
	v_pk_mul_f32 v[44:45], v[34:35], v[154:155]
	v_pk_mul_f32 v[46:47], v[32:33], v[152:153]
	v_pk_fma_f32 v[42:43], v[36:37], v[152:153], v[42:43] neg_lo:[0,0,1] neg_hi:[0,0,1]
	v_pk_fma_f32 v[40:41], v[38:39], v[154:155], v[40:41] neg_lo:[0,0,1] neg_hi:[0,0,1]
	v_pk_fma_f32 v[46:47], v[36:37], v[148:149], v[46:47]
	v_pk_fma_f32 v[44:45], v[38:39], v[150:151], v[44:45]
	v_cndmask_b32_e64 v38, v40, v38, s[8:9]
	v_cndmask_b32_e64 v36, v42, v36, s[8:9]
	v_cndmask_b32_e64 v40, v44, v34, s[8:9]
	v_cndmask_b32_e64 v35, v45, v35, s[8:9]
	v_cndmask_b32_e64 v34, v46, v32, s[8:9]
	v_cndmask_b32_e64 v39, v41, v39, s[8:9]
	v_cndmask_b32_e64 v37, v43, v37, s[8:9]
	v_cndmask_b32_e64 v41, v47, v33, s[8:9]
	v_cvt_pk_bf16_f32 v32, v36, v37
	v_cvt_pk_bf16_f32 v33, v38, v39
	v_cvt_pk_bf16_f32 v34, v34, v41
	v_cvt_pk_bf16_f32 v35, v40, v35
	v_add_u32_e32 v36, 0x18100, v65
	v_pk_mul_f32 v[24:25], v[24:25], v[66:67] op_sel_hi:[1,0]
	v_pk_mul_f32 v[26:27], v[26:27], v[66:67] op_sel_hi:[1,0]
	global_store_dwordx4 v36, v[32:35], s[66:67]
	v_pk_mul_f32 v[28:29], v[28:29], v[66:67] op_sel_hi:[1,0]
	v_pk_mul_f32 v[30:31], v[30:31], v[66:67] op_sel_hi:[1,0]
	v_pk_mul_f32 v[32:33], v[26:27], v[142:143]
	v_pk_mul_f32 v[34:35], v[24:25], v[140:141]
	v_pk_mul_f32 v[36:37], v[26:27], v[146:147]
	v_pk_mul_f32 v[38:39], v[24:25], v[144:145]
	v_fmamk_f32 v64, v195, 0x3b000000, v196
	v_pk_fma_f32 v[34:35], v[28:29], v[144:145], v[34:35] neg_lo:[0,0,1] neg_hi:[0,0,1]
	v_pk_fma_f32 v[32:33], v[30:31], v[146:147], v[32:33] neg_lo:[0,0,1] neg_hi:[0,0,1]
	v_pk_fma_f32 v[38:39], v[28:29], v[140:141], v[38:39]
	v_pk_fma_f32 v[36:37], v[30:31], v[142:143], v[36:37]
	v_rsq_f32_e32 v64, v64
	v_cndmask_b32_e64 v30, v32, v30, s[8:9]
	v_cndmask_b32_e64 v28, v34, v28, s[8:9]
	v_cndmask_b32_e64 v32, v36, v26, s[8:9]
	v_cndmask_b32_e64 v27, v37, v27, s[8:9]
	v_cndmask_b32_e64 v26, v38, v24, s[8:9]
	v_cndmask_b32_e64 v31, v33, v31, s[8:9]
	v_cndmask_b32_e64 v29, v35, v29, s[8:9]
	v_cndmask_b32_e64 v33, v39, v25, s[8:9]
	v_cvt_pk_bf16_f32 v24, v28, v29
	v_cvt_pk_bf16_f32 v25, v30, v31
	v_cvt_pk_bf16_f32 v26, v26, v33
	v_cvt_pk_bf16_f32 v27, v32, v27
	v_add_u32_e32 v28, 0x30000, v65
	v_pk_mul_f32 v[16:17], v[16:17], v[66:67] op_sel_hi:[1,0]
	v_pk_mul_f32 v[18:19], v[18:19], v[66:67] op_sel_hi:[1,0]
	global_store_dwordx4 v28, v[24:27], s[66:67]
	v_pk_mul_f32 v[20:21], v[20:21], v[66:67] op_sel_hi:[1,0]
	v_pk_mul_f32 v[22:23], v[22:23], v[66:67] op_sel_hi:[1,0]
	v_pk_mul_f32 v[24:25], v[18:19], v[142:143]
	v_pk_mul_f32 v[26:27], v[16:17], v[140:141]
	v_pk_mul_f32 v[28:29], v[18:19], v[146:147]
	v_pk_mul_f32 v[30:31], v[16:17], v[144:145]
	v_pk_fma_f32 v[26:27], v[20:21], v[144:145], v[26:27] neg_lo:[0,0,1] neg_hi:[0,0,1]
	v_pk_fma_f32 v[24:25], v[22:23], v[146:147], v[24:25] neg_lo:[0,0,1] neg_hi:[0,0,1]
	v_pk_fma_f32 v[30:31], v[20:21], v[140:141], v[30:31]
	v_pk_fma_f32 v[28:29], v[22:23], v[142:143], v[28:29]
	v_mul_f32_e32 v64, 0x3dd53b94, v64
	v_cndmask_b32_e64 v22, v24, v22, s[8:9]
	v_cndmask_b32_e64 v20, v26, v20, s[8:9]
	v_cndmask_b32_e64 v24, v28, v18, s[8:9]
	v_cndmask_b32_e64 v19, v29, v19, s[8:9]
	v_cndmask_b32_e64 v18, v30, v16, s[8:9]
	v_cndmask_b32_e64 v23, v25, v23, s[8:9]
	v_cndmask_b32_e64 v21, v27, v21, s[8:9]
	v_cndmask_b32_e64 v25, v31, v17, s[8:9]
	v_cvt_pk_bf16_f32 v16, v20, v21
	v_cvt_pk_bf16_f32 v17, v22, v23
	v_cvt_pk_bf16_f32 v18, v18, v25
	v_cvt_pk_bf16_f32 v19, v24, v19
	v_add_u32_e32 v20, 0x30100, v65
	v_pk_mul_f32 v[8:9], v[8:9], v[64:65] op_sel_hi:[1,0]
	v_pk_mul_f32 v[10:11], v[10:11], v[64:65] op_sel_hi:[1,0]
	global_store_dwordx4 v20, v[16:19], s[66:67]
	v_pk_mul_f32 v[12:13], v[12:13], v[64:65] op_sel_hi:[1,0]
	v_pk_mul_f32 v[14:15], v[14:15], v[64:65] op_sel_hi:[1,0]
	v_pk_mul_f32 v[16:17], v[10:11], v[134:135]
	v_pk_mul_f32 v[18:19], v[8:9], v[132:133]
	v_pk_mul_f32 v[20:21], v[10:11], v[138:139]
	v_pk_mul_f32 v[22:23], v[8:9], v[136:137]
	v_pk_fma_f32 v[18:19], v[12:13], v[136:137], v[18:19] neg_lo:[0,0,1] neg_hi:[0,0,1]
	v_pk_fma_f32 v[16:17], v[14:15], v[138:139], v[16:17] neg_lo:[0,0,1] neg_hi:[0,0,1]
	v_pk_fma_f32 v[22:23], v[12:13], v[132:133], v[22:23]
	v_pk_fma_f32 v[20:21], v[14:15], v[134:135], v[20:21]
	v_cndmask_b32_e64 v14, v16, v14, s[8:9]
	v_cndmask_b32_e64 v12, v18, v12, s[8:9]
	v_cndmask_b32_e64 v16, v20, v10, s[8:9]
	v_cndmask_b32_e64 v11, v21, v11, s[8:9]
	v_cndmask_b32_e64 v10, v22, v8, s[8:9]
	v_cndmask_b32_e64 v15, v17, v15, s[8:9]
	v_cndmask_b32_e64 v13, v19, v13, s[8:9]
	v_cndmask_b32_e64 v17, v23, v9, s[8:9]
	v_cvt_pk_bf16_f32 v8, v12, v13
	v_cvt_pk_bf16_f32 v9, v14, v15
	v_cvt_pk_bf16_f32 v10, v10, v17
	v_cvt_pk_bf16_f32 v11, v16, v11
	v_add_u32_e32 v12, 0x48000, v65
	v_pk_mul_f32 v[0:1], v[0:1], v[64:65] op_sel_hi:[1,0]
	global_store_dwordx4 v12, v[8:11], s[66:67]
	v_pk_mul_f32 v[4:5], v[4:5], v[64:65] op_sel_hi:[1,0]
	v_pk_mul_f32 v[2:3], v[2:3], v[64:65] op_sel_hi:[1,0]
	v_pk_mul_f32 v[10:11], v[0:1], v[132:133]
	v_pk_mul_f32 v[6:7], v[6:7], v[64:65] op_sel_hi:[1,0]
	v_pk_mul_f32 v[8:9], v[2:3], v[134:135]
	v_pk_fma_f32 v[10:11], v[4:5], v[136:137], v[10:11] neg_lo:[0,0,1] neg_hi:[0,0,1]
	v_pk_mul_f32 v[12:13], v[2:3], v[138:139]
	v_pk_mul_f32 v[14:15], v[0:1], v[136:137]
	v_pk_fma_f32 v[8:9], v[6:7], v[138:139], v[8:9] neg_lo:[0,0,1] neg_hi:[0,0,1]
	v_pk_fma_f32 v[14:15], v[4:5], v[132:133], v[14:15]
	v_pk_fma_f32 v[12:13], v[6:7], v[134:135], v[12:13]
	v_cndmask_b32_e64 v4, v10, v4, s[8:9]
	v_cndmask_b32_e64 v6, v8, v6, s[8:9]
	v_cndmask_b32_e64 v5, v11, v5, s[8:9]
	v_cndmask_b32_e64 v8, v12, v2, s[8:9]
	v_cndmask_b32_e64 v3, v13, v3, s[8:9]
	v_cndmask_b32_e64 v2, v14, v0, s[8:9]
	v_cvt_pk_bf16_f32 v0, v4, v5
	v_add_u32_e32 v4, 0x48100, v65
	v_cndmask_b32_e64 v7, v9, v7, s[8:9]
	v_cndmask_b32_e64 v9, v15, v1, s[8:9]
	v_cvt_pk_bf16_f32 v1, v6, v7
	v_cvt_pk_bf16_f32 v2, v2, v9
	v_cvt_pk_bf16_f32 v3, v8, v3
	global_store_dwordx4 v4, v[0:3], s[66:67]
	s_and_b64 vcc, exec, s[6:7]
	s_mov_b64 s[6:7], -1
	v_add_u32_e32 v0, 0x80, v130
	s_cbranch_vccnz .LBB0_737
	s_andn2_b64 vcc, exec, s[64:65]
	s_cbranch_vccnz .LBB0_736
	s_barrier
	s_branch .LBB0_736
